# lean GEMM load segments + removed two compiler-inserted vmcnt(0) waits that serialized next-tile LDS-DMA against LDS stage accesses in the dilated and MoBA attention loops
# speedup vs baseline: 1.0092x; 1.0005x over previous
.LBB0_88:
	s_waitcnt lgkmcnt(0)
	v_mfma_f32_32x32x16_bf16 v[66:81], v[66:69], v[82:85], 0
	s_xor_b64 s[10:11], s[20:21], -1
	s_andn2_b64 vcc, exec, s[20:21]
	ds_write_b128 v243, v[114:117]
	ds_write_b128 v244, v[118:121] offset:256
	ds_write_b128 v245, v[122:125] offset:2048
	ds_write_b128 v246, v[126:129] offset:2304
	ds_write_b128 v243, v[130:133] offset:4096
	ds_write_b128 v244, v[134:137] offset:4352
	ds_write_b128 v245, v[138:141] offset:6144
	ds_write_b128 v246, v[142:145] offset:6400
	v_mfma_f32_32x32x16_bf16 v[66:81], v[170:173], v[86:89], v[66:81]
	v_mfma_f32_32x32x16_bf16 v[66:81], v[158:161], v[90:93], v[66:81]
	v_mfma_f32_32x32x16_bf16 v[66:81], v[162:165], v[94:97], v[66:81]
	v_mfma_f32_32x32x16_bf16 v[66:81], v[154:157], v[98:101], v[66:81]
	v_mfma_f32_32x32x16_bf16 v[66:81], v[166:169], v[102:105], v[66:81]
	v_mfma_f32_32x32x16_bf16 v[66:81], v[150:153], v[106:109], v[66:81]
	v_mfma_f32_32x32x16_bf16 v[66:81], v[146:149], v[110:113], v[66:81]
	s_cbranch_vccnz .LBB0_90
	v_mul_lo_u32 v64, s44, v221
	v_add_u32_e32 v116, s43, v64
	v_med3_i32 v64, v116, 0, v232
	s_lshl_b32 s20, s44, 2
	v_mul_u32_u24_e32 v64, 0x3000, v64
	v_add_u32_e32 v122, s20, v116
	v_lshl_add_u64 v[114:115], v[202:203], 0, v[64:65]
	v_med3_i32 v64, v122, 0, v232
	v_mul_u32_u24_e32 v64, 0x3000, v64
	v_add_u32_e32 v124, s20, v122
	v_lshl_add_u64 v[118:119], v[202:203], 0, v[64:65]
	v_med3_i32 v64, v124, 0, v232
	v_mul_u32_u24_e32 v64, 0x3000, v64
	v_add_u32_e32 v130, s20, v124
	v_lshl_add_u64 v[122:123], v[202:203], 0, v[64:65]
	v_med3_i32 v64, v130, 0, v232
	v_mul_u32_u24_e32 v64, 0x3000, v64
	v_add_u32_e32 v132, s20, v130
	v_lshl_add_u64 v[126:127], v[202:203], 0, v[64:65]
	v_med3_i32 v64, v132, 0, v232
	v_mul_u32_u24_e32 v64, 0x3000, v64
	v_add_u32_e32 v138, s20, v132
	v_lshl_add_u64 v[130:131], v[202:203], 0, v[64:65]
	v_med3_i32 v64, v138, 0, v232
	v_mul_u32_u24_e32 v64, 0x3000, v64
	v_add_u32_e32 v140, s20, v138
	v_lshl_add_u64 v[134:135], v[202:203], 0, v[64:65]
	v_med3_i32 v64, v140, 0, v232
	v_mul_u32_u24_e32 v64, 0x3000, v64
	v_lshl_add_u64 v[138:139], v[202:203], 0, v[64:65]
	v_add_u32_e32 v64, s20, v140
	v_med3_i32 v64, v64, 0, v232
	v_mul_u32_u24_e32 v64, 0x3000, v64
	v_lshl_add_u64 v[142:143], v[202:203], 0, v[64:65]
	global_load_dwordx4 v[114:117], v[114:115], off
	s_nop 0
	global_load_dwordx4 v[118:121], v[118:119], off
	s_nop 0
	global_load_dwordx4 v[122:125], v[122:123], off
	s_nop 0
	global_load_dwordx4 v[126:129], v[126:127], off
	s_nop 0
	global_load_dwordx4 v[130:133], v[130:131], off
	s_nop 0
	global_load_dwordx4 v[134:137], v[134:135], off
	s_nop 0
	global_load_dwordx4 v[138:141], v[138:139], off
	s_nop 0
	global_load_dwordx4 v[142:145], v[142:143], off

.LBB0_141:
	v_exp_f32_e32 v64, v66
	s_nop 7
	v_exp_f32_e32 v96, v67
	v_exp_f32_e32 v97, v68
	v_exp_f32_e32 v98, v69
	v_exp_f32_e32 v99, v70
	v_cvt_pk_bf16_f32 v66, v64, v96
	v_add_f32_e32 v64, 0, v64
	v_exp_f32_e32 v100, v71
	v_add_f32_e32 v64, v96, v64
	v_exp_f32_e32 v101, v72
	v_add_f32_e32 v64, v97, v64
	v_exp_f32_e32 v102, v73
	v_add_f32_e32 v64, v98, v64
	v_exp_f32_e32 v74, v74
	v_add_f32_e32 v64, v99, v64
	v_exp_f32_e32 v75, v75
	v_add_f32_e32 v64, v100, v64
	v_exp_f32_e32 v106, v160
	v_exp_f32_e32 v107, v161
	v_exp_f32_e32 v76, v76
	v_add_f32_e32 v64, v101, v64
	v_exp_f32_e32 v77, v77
	v_add_f32_e32 v64, v102, v64
	v_exp_f32_e32 v108, v162
	v_exp_f32_e32 v78, v78
	v_add_f32_e32 v64, v74, v64
	v_exp_f32_e32 v109, v163
	v_exp_f32_e32 v79, v79
	v_add_f32_e32 v64, v75, v64
	v_exp_f32_e32 v110, v164
	v_cvt_pk_bf16_f32 v96, v106, v107
	v_add_f32_e32 v106, 0, v106
	v_add_f32_e32 v64, v76, v64
	v_exp_f32_e32 v111, v165
	v_add_f32_e32 v106, v107, v106
	v_exp_f32_e32 v103, v158
	v_add_f32_e32 v64, v77, v64
	v_exp_f32_e32 v158, v166
	v_add_f32_e32 v106, v108, v106
	v_exp_f32_e32 v104, v159
	v_add_f32_e32 v64, v78, v64
	v_exp_f32_e32 v159, v167
	v_add_f32_e32 v106, v109, v106
	v_cvt_pk_bf16_f32 v72, v78, v79
	v_add_f32_e32 v64, v79, v64
	v_exp_f32_e32 v78, v168
	v_exp_f32_e32 v79, v169
	v_add_f32_e32 v106, v110, v106
	v_add_f32_e32 v106, v111, v106
	v_cvt_pk_bf16_f32 v68, v99, v100
	v_exp_f32_e32 v100, v170
	v_add_f32_e32 v106, v158, v106
	v_cvt_pk_bf16_f32 v69, v101, v102
	v_exp_f32_e32 v101, v171
	v_add_f32_e32 v106, v159, v106
	v_cvt_pk_bf16_f32 v70, v74, v75
	v_exp_f32_e32 v102, v172
	v_cvt_pk_bf16_f32 v74, v78, v79
	v_add_f32_e32 v78, v78, v106
	v_cvt_pk_bf16_f32 v73, v103, v104
	v_add_f32_e32 v64, v103, v64
	v_exp_f32_e32 v103, v173
	v_add_f32_e32 v78, v79, v78
	v_add_f32_e32 v64, v104, v64
	v_exp_f32_e32 v104, v174
	v_add_f32_e32 v78, v100, v78
	v_exp_f32_e32 v105, v175
	v_add_f32_e32 v78, v101, v78
	v_add_f32_e32 v78, v102, v78
	v_add_f32_e32 v78, v103, v78
	v_add_f32_e32 v78, v104, v78
	v_add_f32_e32 v64, v202, v64
	v_add_f32_e32 v78, v105, v78
	v_add_f32_e32 v202, v64, v78
	v_add3_u32 v64, s49, v193, v195
	v_add3_u32 v64, v64, v196, v197
	v_add_u32_e32 v78, v64, v198
	v_cvt_pk_bf16_f32 v67, v97, v98
	v_cvt_pk_bf16_f32 v71, v76, v77
	v_cvt_pk_bf16_f32 v75, v100, v101
	v_cvt_pk_bf16_f32 v76, v102, v103
	v_cvt_pk_bf16_f32 v77, v104, v105
	v_cvt_pk_bf16_f32 v97, v108, v109
	v_cvt_pk_bf16_f32 v98, v110, v111
	v_cvt_pk_bf16_f32 v99, v158, v159
	v_add_u32_e32 v64, v64, v199
	ds_read_b64_tr_b16 v[100:101], v78 offset:16384
	ds_read_b64_tr_b16 v[104:105], v78 offset:20480
	ds_read_b64_tr_b16 v[108:109], v78 offset:20992
	ds_read_b64_tr_b16 v[158:159], v78 offset:16896
	ds_read_b64_tr_b16 v[102:103], v64 offset:18432
	ds_read_b64_tr_b16 v[106:107], v64 offset:22528
	ds_read_b64_tr_b16 v[110:111], v64 offset:23040
	ds_read_b64_tr_b16 v[160:161], v64 offset:18944
	s_waitcnt lgkmcnt(0)
	s_waitcnt lgkmcnt(3)
	v_mfma_f32_32x32x16_bf16 v[48:63], v[100:103], v[66:69], v[48:63]
	s_waitcnt lgkmcnt(0)
	v_mfma_f32_32x32x16_bf16 v[32:47], v[158:161], v[66:69], v[32:47]
	v_mfma_f32_32x32x16_bf16 v[48:63], v[104:107], v[70:73], v[48:63]
	v_mfma_f32_32x32x16_bf16 v[32:47], v[108:111], v[70:73], v[32:47]
	ds_read_b64_tr_b16 v[100:101], v78 offset:17408
	ds_read_b64_tr_b16 v[104:105], v78 offset:21504
	ds_read_b64_tr_b16 v[108:109], v78 offset:22016
	ds_read_b64_tr_b16 v[158:159], v78 offset:17920
	ds_read_b64_tr_b16 v[102:103], v64 offset:19456
	ds_read_b64_tr_b16 v[106:107], v64 offset:23552
	ds_read_b64_tr_b16 v[110:111], v64 offset:24064
	ds_read_b64_tr_b16 v[160:161], v64 offset:19968
	s_waitcnt lgkmcnt(0)
	s_waitcnt lgkmcnt(3)
	v_mfma_f32_32x32x16_bf16 v[16:31], v[100:103], v[66:69], v[16:31]
	s_waitcnt lgkmcnt(0)
	v_mfma_f32_32x32x16_bf16 v[0:15], v[158:161], v[66:69], v[0:15]
	v_mfma_f32_32x32x16_bf16 v[16:31], v[104:107], v[70:73], v[16:31]
	v_mfma_f32_32x32x16_bf16 v[0:15], v[108:111], v[70:73], v[0:15]
	ds_read_b64_tr_b16 v[66:67], v78 offset:24576
	ds_read_b64_tr_b16 v[70:71], v78 offset:28672
	ds_read_b64_tr_b16 v[100:101], v78 offset:29184
	ds_read_b64_tr_b16 v[104:105], v78 offset:25088
	ds_read_b64_tr_b16 v[68:69], v64 offset:26624
	ds_read_b64_tr_b16 v[72:73], v64 offset:30720
	ds_read_b64_tr_b16 v[102:103], v64 offset:31232
	ds_read_b64_tr_b16 v[106:107], v64 offset:27136
	s_waitcnt lgkmcnt(0)
	s_waitcnt lgkmcnt(3)
	v_mfma_f32_32x32x16_bf16 v[48:63], v[66:69], v[96:99], v[48:63]
	s_waitcnt lgkmcnt(0)
	v_mfma_f32_32x32x16_bf16 v[32:47], v[104:107], v[96:99], v[32:47]
	v_mfma_f32_32x32x16_bf16 v[48:63], v[70:73], v[74:77], v[48:63]
	v_mfma_f32_32x32x16_bf16 v[32:47], v[100:103], v[74:77], v[32:47]
	ds_read_b64_tr_b16 v[66:67], v78 offset:25600
	ds_read_b64_tr_b16 v[70:71], v78 offset:29696
	ds_read_b64_tr_b16 v[100:101], v78 offset:30208
	ds_read_b64_tr_b16 v[104:105], v78 offset:26112
	ds_read_b64_tr_b16 v[68:69], v64 offset:27648
	ds_read_b64_tr_b16 v[72:73], v64 offset:31744
	ds_read_b64_tr_b16 v[102:103], v64 offset:32256
	ds_read_b64_tr_b16 v[106:107], v64 offset:28160
	s_waitcnt lgkmcnt(0)
	s_waitcnt lgkmcnt(3)
	v_mfma_f32_32x32x16_bf16 v[16:31], v[66:69], v[96:99], v[16:31]
	s_waitcnt lgkmcnt(0)
	v_mfma_f32_32x32x16_bf16 v[0:15], v[104:107], v[96:99], v[0:15]
	v_mfma_f32_32x32x16_bf16 v[16:31], v[70:73], v[74:77], v[16:31]
	v_mfma_f32_32x32x16_bf16 v[0:15], v[100:103], v[74:77], v[0:15]
	s_and_b64 vcc, exec, s[20:21]
	s_mov_b64 s[10:11], -1
	s_cbranch_vccz .LBB0_126
